# v80 + NSA selected/window key loops: per-tile workgroup barrier replaced by group-local LDS progress flags for t>=1, no skew
# speedup vs baseline: 1.0031x; 1.0031x over previous
; DI void phase_attn_nsa(const Params& P, bf16_t* og, unsigned char* smem, int L, int G) {
;     ...
;       for (int j = 0; j <= jhi; ++j) {
;         const int key0 = j * 64, cb = j & 1;
;         __syncthreads();
;         if (j < jhi) kv64_store(R, sK + (cb ^ 1) * KVB64, sVt + (cb ^ 1) * KVB64, tid);
.LBB0_1345:
	s_and_b32 s5, s0, 1
	s_add_i32 s98, s0, 1
	v_mov_b32_e32 v254, s98
	s_cmp_eq_u32 s0, 0
	s_cbranch_scc0 .Lmy_nsasel_spin
	s_waitcnt lgkmcnt(0)
	s_barrier
	s_branch .Lmy_nsasel_go

; #define MFMA(a, b, c) __builtin_amdgcn_mfma_f32_32x32x16_bf16((a), (b), (c), 0, 0, 0)
; DI float shx(float v, int m) { return __shfl_xor(v, m, 64); }
; template <int DQK, bool MASKED, int MODE, class MF>
; DI void attn_step(const bf16_t* sK, const bf16_t* sVt, const bf16x8 (&qf)[DQK / 16], f32x16& o0, f32x16& o1, float& m, float& l,
;                   float sc, const MF& mf, int lane, f32x16 (&s)[2], float invl, bool lanevalid = true) {
;     ...
;   bf16x8 kf[2][DQK / 16];
; #pragma unroll
;   for (int sub = 0; sub < 2; ++sub)
; #pragma unroll
;     for (int ks = 0; ks < DQK / 16; ++ks) kf[sub][ks] = *(const bf16x8*)(sK + (sub * 32 + pr) * KST + ks * 16 + 8 * h);
;   __builtin_amdgcn_sched_barrier(0);
; #pragma unroll
;   for (int q = 0; q < 16; ++q) { s[0][q] = 0.f; s[1][q] = 0.f; }
; #pragma unroll
;   for (int ks = 0; ks < DQK / 16; ++ks) {
;     s[0] = MFMA(kf[0][ks], qf[ks], s[0]);
;     s[1] = MFMA(kf[1][ks], qf[ks], s[1]);
;   }
;   bf16x8 vf[2][2][2];
;   if (MODE != 1) {
; #pragma unroll
;     for (int sub = 0; sub < 2; ++sub)
; #pragma unroll
;       for (int s2 = 0; s2 < 2; ++s2) {
;         vf[sub][s2][0] = *(const bf16x8*)(sVt + r * 72 + sub * 32 + s2 * 16 + 8 * h);
;         vf[sub][s2][1] = *(const bf16x8*)(sVt + (32 + r) * 72 + sub * 32 + s2 * 16 + 8 * h);
;       }
;     __builtin_amdgcn_sched_barrier(0);
;   }
;   float mxr = -3.0e38f;
; #pragma unroll
;   for (int sub = 0; sub < 2; ++sub)
; #pragma unroll
;     for (int q = 0; q < 16; ++q) {
;       if (MASKED) { const int kk = sub * 32 + 16 * (q >> 3) + 8 * h + (q & 7); s[sub][q] = mf(kk) ? s[sub][q] : -3.0e38f; }
;       if (MODE != 2) mxr = fmaxf(mxr, s[sub][q]);
;     }
;   float alpha = 1.f;
;   if (MODE != 2) {
;     float mx = fmaxf(m, mxr * sc);
;     mx = fmaxf(mx, shx(mx, 32));
; DI void phase_attn_nsa(const Params& P, bf16_t* og, unsigned char* smem, int L, int G) {
;     ...
;         if ((selU >> j) & 1u) {
;           const bool lsel = (sel >> j) & 1u;
;           auto mf = [&](int kk) { return lsel && (key0 + kk <= t); };
;           if (key0 + 63 > t0) attn_step<64, true, 0>(sK + cb * KVB64, sVt + cb * KVB64, qf, o0, o1, m, l, sc, mf, lane, s, 0.f);
;           else attn_step<64, false, 0>(sK + cb * KVB64, sVt + cb * KVB64, qf, o0, o1, m, l, sc, mf, lane, s, 0.f, lsel);
.LBB0_1349:
	s_lshr_b32 s1, s2, s0
	s_bitcmp0_b32 s1, 0
	s_cbranch_scc1 .Lmy_nsasel_skip
	v_lshrrev_b32_e32 v0, s0, v183
	s_add_i32 s6, s44, 63
	s_mulk_i32 s5, 0x4800
	v_and_b32_e32 v190, 1, v0
	s_mov_b64 s[0:1], -1
	s_cmp_le_u32 s6, s46
	v_max_f32_e32 v188, v141, v141
	v_add_u32_e32 v189, s5, v153
	v_cmp_eq_u32_e32 vcc, 1, v190
	s_cbranch_scc0 .LBB0_1352
	v_add_u32_e32 v0, s5, v182
	ds_read_b128 v[34:37], v0
	ds_read_b128 v[38:41], v0 offset:32
	ds_read_b128 v[106:109], v0 offset:64
	ds_read_b128 v[110:113], v0 offset:96
	ds_read_b128 v[42:45], v0 offset:4608
	ds_read_b128 v[114:117], v0 offset:4640
	ds_read_b128 v[118:121], v0 offset:4672
	ds_read_b128 v[194:197], v0 offset:4704
	s_waitcnt lgkmcnt(7)
	v_mfma_f32_32x32x16_bf16 v[58:73], v[34:37], v[74:77], 0
	v_add3_u32 v0, v189, v175, v138
	v_add3_u32 v34, v189, v177, v138
	s_waitcnt lgkmcnt(3)
	v_mfma_f32_32x32x16_bf16 v[42:57], v[42:45], v[74:77], 0
	v_mfma_f32_32x32x16_bf16 v[58:73], v[38:41], v[78:81], v[58:73]
	s_waitcnt lgkmcnt(2)
	v_mfma_f32_32x32x16_bf16 v[42:57], v[114:117], v[78:81], v[42:57]
	v_mfma_f32_32x32x16_bf16 v[58:73], v[106:109], v[82:85], v[58:73]
	s_waitcnt lgkmcnt(1)
	v_mfma_f32_32x32x16_bf16 v[42:57], v[118:121], v[82:85], v[42:57]
	v_mfma_f32_32x32x16_bf16 v[58:73], v[110:113], v[86:89], v[58:73]
	ds_read_b128 v[198:201], v0 offset:9216
	ds_read_b128 v[126:129], v0 offset:9248
	ds_read_b128 v[130:133], v34 offset:9216
	ds_read_b128 v[122:125], v34 offset:9248
	ds_read_b128 v[118:121], v0 offset:9280
	ds_read_b128 v[110:113], v0 offset:9312
	ds_read_b128 v[114:117], v34 offset:9280
	ds_read_b128 v[106:109], v34 offset:9312
	s_waitcnt lgkmcnt(8)
	v_mfma_f32_32x32x16_bf16 v[42:57], v[194:197], v[86:89], v[42:57]
	s_nop 1
	v_max3_f32 v0, v58, s8, v59
	v_max3_f32 v0, v0, v60, v61
	v_max3_f32 v0, v0, v62, v63
	v_max3_f32 v0, v0, v64, v65
	v_max3_f32 v0, v0, v66, v67
	v_max3_f32 v0, v0, v68, v69
	v_max3_f32 v0, v0, v70, v71
	v_max3_f32 v0, v0, v72, v73
	s_nop 1
	v_max3_f32 v0, v0, v42, v43
	v_max3_f32 v0, v0, v44, v45
	v_max3_f32 v0, v0, v46, v47
	v_max3_f32 v0, v0, v48, v49
	v_max3_f32 v0, v0, v50, v51
	v_max3_f32 v0, v0, v52, v53
	v_max3_f32 v0, v0, v54, v55
	v_max3_f32 v0, v0, v56, v57
	v_mul_f32_e32 v0, 0x3e38aa3b, v0
	v_max_f32_e32 v0, v188, v0
	ds_bpermute_b32 v34, v173, v0
	s_mov_b64 s[0:1], 0
	s_waitcnt lgkmcnt(0)
	s_mov_b64 s[100:101], exec
	s_mov_b64 exec, 1
	ds_write_b32 v252, v254
	s_mov_b64 exec, s[100:101]
	v_max_f32_e32 v34, v34, v34
	v_max_f32_e32 v34, v0, v34
	v_cndmask_b32_e64 v191, v167, -v34, vcc
	v_fmamk_f32 v35, v58, 0x3e38aa3b, v191
	v_fmamk_f32 v36, v59, 0x3e38aa3b, v191
	v_exp_f32_e32 v58, v35
	v_fmamk_f32 v37, v60, 0x3e38aa3b, v191
	v_exp_f32_e32 v59, v36
	v_exp_f32_e32 v60, v37
	v_fmamk_f32 v35, v61, 0x3e38aa3b, v191
	v_exp_f32_e32 v61, v35
	v_add_f32_e32 v36, 0, v58
	v_fmamk_f32 v35, v62, 0x3e38aa3b, v191
	v_add_f32_e32 v36, v59, v36
	v_exp_f32_e32 v62, v35
	v_fmamk_f32 v35, v63, 0x3e38aa3b, v191
	v_add_f32_e32 v36, v60, v36
	v_exp_f32_e32 v63, v35
	v_fmamk_f32 v35, v64, 0x3e38aa3b, v191
	v_exp_f32_e32 v64, v35
	v_add_f32_e32 v35, v61, v36
	v_fmamk_f32 v36, v65, 0x3e38aa3b, v191
	v_exp_f32_e32 v65, v36
	v_fmamk_f32 v36, v66, 0x3e38aa3b, v191
	v_add_f32_e32 v35, v62, v35
	v_exp_f32_e32 v203, v36
	v_fmamk_f32 v36, v67, 0x3e38aa3b, v191
	v_add_f32_e32 v35, v63, v35
	v_exp_f32_e32 v204, v36
	v_fmamk_f32 v36, v68, 0x3e38aa3b, v191
	v_add_f32_e32 v35, v64, v35
	v_exp_f32_e32 v205, v36
	v_fmamk_f32 v36, v69, 0x3e38aa3b, v191
	v_add_f32_e32 v35, v65, v35
	v_exp_f32_e32 v206, v36
	v_fmamk_f32 v36, v70, 0x3e38aa3b, v191
	v_add_f32_e32 v35, v203, v35
	v_exp_f32_e32 v207, v36
	v_fmamk_f32 v36, v71, 0x3e38aa3b, v191
	v_add_f32_e32 v35, v204, v35
	v_exp_f32_e32 v208, v36
	v_fmamk_f32 v36, v72, 0x3e38aa3b, v191
	v_add_f32_e32 v35, v205, v35
	v_exp_f32_e32 v209, v36
	v_fmamk_f32 v36, v73, 0x3e38aa3b, v191
	v_add_f32_e32 v35, v206, v35
	v_exp_f32_e32 v210, v36
	v_fmamk_f32 v36, v42, 0x3e38aa3b, v191
	v_add_f32_e32 v35, v207, v35
	v_exp_f32_e32 v211, v36
	v_fmamk_f32 v36, v43, 0x3e38aa3b, v191
	v_add_f32_e32 v35, v208, v35
	v_exp_f32_e32 v212, v36
	v_fmamk_f32 v36, v44, 0x3e38aa3b, v191
	v_add_f32_e32 v35, v209, v35
	v_exp_f32_e32 v213, v36
	v_fmamk_f32 v36, v45, 0x3e38aa3b, v191
	v_add_f32_e32 v35, v210, v35
	v_exp_f32_e32 v214, v36
	v_fmamk_f32 v36, v46, 0x3e38aa3b, v191
	v_add_f32_e32 v35, v211, v35
	v_exp_f32_e32 v215, v36
	v_fmamk_f32 v36, v47, 0x3e38aa3b, v191
	v_cndmask_b32_e32 v0, v141, v34, vcc
	v_add_f32_e32 v35, v212, v35
	v_exp_f32_e32 v216, v36
	v_fmamk_f32 v36, v48, 0x3e38aa3b, v191
	v_sub_f32_e32 v34, v141, v0
	v_add_f32_e32 v35, v213, v35
	v_exp_f32_e32 v217, v36
	v_add_f32_e32 v35, v214, v35
	v_exp_f32_e32 v202, v34
	v_add_f32_e32 v35, v215, v35
	v_add_f32_e32 v35, v216, v35
	v_add_f32_e32 v218, v217, v35
	v_fmamk_f32 v35, v49, 0x3e38aa3b, v191
	v_fmamk_f32 v34, v50, 0x3e38aa3b, v191
	v_exp_f32_e32 v219, v35
	v_exp_f32_e32 v220, v34
	v_pk_mul_f32 v[32:33], v[32:33], v[202:203] op_sel_hi:[1,0]
	v_pk_mul_f32 v[30:31], v[30:31], v[202:203] op_sel_hi:[1,0]
	v_pk_mul_f32 v[28:29], v[28:29], v[202:203] op_sel_hi:[1,0]
	v_pk_mul_f32 v[26:27], v[26:27], v[202:203] op_sel_hi:[1,0]
	v_pk_mul_f32 v[24:25], v[24:25], v[202:203] op_sel_hi:[1,0]
	v_pk_mul_f32 v[22:23], v[22:23], v[202:203] op_sel_hi:[1,0]
	v_pk_mul_f32 v[20:21], v[20:21], v[202:203] op_sel_hi:[1,0]
	v_pk_mul_f32 v[18:19], v[18:19], v[202:203] op_sel_hi:[1,0]
	v_cvt_pk_bf16_f32 v194, v58, v59
	v_cvt_pk_bf16_f32 v195, v60, v61
	v_cvt_pk_bf16_f32 v196, v62, v63
	v_cvt_pk_bf16_f32 v197, v64, v65
	v_pk_mul_f32 v[16:17], v[16:17], v[202:203] op_sel_hi:[1,0]
	v_pk_mul_f32 v[14:15], v[14:15], v[202:203] op_sel_hi:[1,0]
; #define MFMA(a, b, c) __builtin_amdgcn_mfma_f32_32x32x16_bf16((a), (b), (c), 0, 0, 0)
; DI unsigned pack2(float a, float b) { f32x2_t v = {a, b}; bf16x2_t r = __builtin_convertvector(v, bf16x2_t); return __builtin_bit_cast(unsigned, r); }
; DI float fexp2(float x) { return __builtin_amdgcn_exp2f(x); }
; DI float shx(float v, int m) { return __shfl_xor(v, m, 64); }
; template <int DQK, bool MASKED, int MODE, class MF>
; DI void attn_step(const bf16_t* sK, const bf16_t* sVt, const bf16x8 (&qf)[DQK / 16], f32x16& o0, f32x16& o1, float& m, float& l,
;                   float sc, const MF& mf, int lane, f32x16 (&s)[2], float invl, bool lanevalid = true) {
;     ...
; #pragma unroll
;   for (int sub = 0; sub < 2; ++sub)
; #pragma unroll
;     for (int q = 0; q < 16; ++q) {
;       float pv = fexp2(__builtin_fmaf(s[sub][q], sc, -moff));
;       if (MASKED && MODE != 0) pv = (s[sub][q] > -1.0e38f) ? pv : 0.f;
;       if (MODE == 2) pv *= invl;
;       s[sub][q] = pv;
;       ps += pv;
;     }
;   if (MODE != 2) {
;     ps += shx(ps, 32);
;     l = l * alpha + ps;
;   }
;   if (MODE == 1) return;
;   if (MODE == 0) {
; #pragma unroll
;     for (int q = 0; q < 16; ++q) { o0[q] *= alpha; o1[q] *= alpha; }
;   }
; #pragma unroll
;   for (int sub = 0; sub < 2; ++sub)
; #pragma unroll
;     for (int s2 = 0; s2 < 2; ++s2) {
;       union { bf16x8 v; unsigned u[4]; } pb;
; #pragma unroll
;       for (int e = 0; e < 4; ++e) pb.u[e] = pack2(s[sub][8 * s2 + 2 * e], s[sub][8 * s2 + 2 * e + 1]);
;       o0 = MFMA(vf[sub][s2][0], pb.v, o0);
;       o1 = MFMA(vf[sub][s2][1], pb.v, o1);
;     }
; DI void phase_attn_nsa(const Params& P, bf16_t* og, unsigned char* smem, int L, int G) {
;     ...
;           auto mf = [&](int kk) { return lsel && (key0 + kk <= t); };
;           if (key0 + 63 > t0) attn_step<64, true, 0>(sK + cb * KVB64, sVt + cb * KVB64, qf, o0, o1, m, l, sc, mf, lane, s, 0.f);
	v_mfma_f32_32x32x16_bf16 v[18:33], v[198:201], v[194:197], v[18:33]
	v_mul_f32_e64 v12, v12, v202
	v_mul_f32_e64 v13, v13, v202
	v_mul_f32_e64 v10, v10, v202
	v_mul_f32_e64 v11, v11, v202
	v_mul_f32_e64 v8, v8, v202
	v_mul_f32_e64 v9, v9, v202
	v_pk_mul_f32 v[6:7], v[6:7], v[202:203] op_sel_hi:[1,0]
	v_pk_mul_f32 v[4:5], v[4:5], v[202:203] op_sel_hi:[1,0]
	v_pk_mul_f32 v[2:3], v[2:3], v[202:203] op_sel_hi:[1,0]
	v_fmamk_f32 v51, v51, 0x3e38aa3b, v191
	v_add_f32_e32 v50, v219, v218
	v_mfma_f32_32x32x16_bf16 v[2:17], v[130:133], v[194:197], v[2:17]
	v_cvt_pk_bf16_f32 v130, v203, v204
	v_cvt_pk_bf16_f32 v131, v205, v206
	v_cvt_pk_bf16_f32 v132, v207, v208
	v_cvt_pk_bf16_f32 v133, v209, v210
	v_add_f32_e32 v50, v220, v50
	v_fmamk_f32 v55, v55, 0x3e38aa3b, v191
	v_exp_f32_e32 v55, v55
	v_mfma_f32_32x32x16_bf16 v[18:33], v[126:129], v[130:133], v[18:33]
	v_exp_f32_e32 v126, v51
	v_fmamk_f32 v51, v52, 0x3e38aa3b, v191
	v_exp_f32_e32 v127, v51
	v_fmamk_f32 v51, v53, 0x3e38aa3b, v191
	v_exp_f32_e32 v128, v51
	v_add_f32_e32 v50, v126, v50
	v_add_f32_e32 v50, v127, v50
	v_mfma_f32_32x32x16_bf16 v[2:17], v[122:125], v[130:133], v[2:17]
	v_add_f32_e32 v122, v128, v50
	v_fmamk_f32 v50, v54, 0x3e38aa3b, v191
	v_exp_f32_e32 v54, v50
	v_fmamk_f32 v56, v56, 0x3e38aa3b, v191
	v_exp_f32_e32 v56, v56
	v_fmac_f32_e32 v191, 0x3e38aa3b, v57
	v_cvt_pk_bf16_f32 v50, v211, v212
	v_cvt_pk_bf16_f32 v51, v213, v214
	v_cvt_pk_bf16_f32 v52, v215, v216
	v_cvt_pk_bf16_f32 v53, v217, v219
	v_exp_f32_e32 v57, v191
	s_nop 0
	v_mfma_f32_32x32x16_bf16 v[18:33], v[118:121], v[50:53], v[18:33]
	v_add_f32_e32 v118, v54, v122
	v_cvt_pk_bf16_f32 v54, v54, v55
	v_mfma_f32_32x32x16_bf16 v[2:17], v[114:117], v[50:53], v[2:17]
	v_add_f32_e32 v50, v55, v118
	v_add_f32_e32 v50, v56, v50
	v_add_f32_e32 v50, v57, v50
	v_cvt_pk_bf16_f32 v52, v220, v126
	v_cvt_pk_bf16_f32 v53, v127, v128
	v_cvt_pk_bf16_f32 v55, v56, v57
	s_nop 1
	v_mfma_f32_32x32x16_bf16 v[18:33], v[110:113], v[52:55], v[18:33]
	v_mfma_f32_32x32x16_bf16 v[2:17], v[106:109], v[52:55], v[2:17]
	v_fma_f32 v50, v185, v202, v50
	s_nop 11
	v_mov_b32_e32 v141, v0
	v_mov_b32_e32 v185, v50
	s_branch .LBB0_1355
.LBB0_1352:
	s_andn2_b64 vcc, exec, s[0:1]
	s_cbranch_vccnz .LBB0_1354
	v_add_u32_e32 v0, s5, v172
	s_nop 6
	ds_read_b128 v[34:37], v0
	s_nop 0
	ds_read_b128 v[66:69], v0 offset:32
	ds_read_b128 v[70:73], v0 offset:64
	ds_read_b128 v[106:109], v0 offset:96
	ds_read_b128 v[38:41], v0 offset:4608
	ds_read_b128 v[110:113], v0 offset:4640
	ds_read_b128 v[114:117], v0 offset:4672
	ds_read_b128 v[194:197], v0 offset:4704
	v_cmp_eq_u32_e32 vcc, 1, v190
	s_waitcnt lgkmcnt(7)
	v_mfma_f32_32x32x16_bf16 v[50:65], v[34:37], v[74:77], 0
	v_lshlrev_b32_e32 v0, 1, v171
	s_waitcnt lgkmcnt(3)
	v_mfma_f32_32x32x16_bf16 v[34:49], v[38:41], v[74:77], 0
	v_mfma_f32_32x32x16_bf16 v[50:65], v[66:69], v[78:81], v[50:65]
	s_waitcnt lgkmcnt(2)
	v_mfma_f32_32x32x16_bf16 v[34:49], v[110:113], v[78:81], v[34:49]
	v_mfma_f32_32x32x16_bf16 v[50:65], v[70:73], v[82:85], v[50:65]
	v_add3_u32 v70, v189, v175, v0
	v_add3_u32 v0, v189, v177, v0
	s_waitcnt lgkmcnt(1)
	v_mfma_f32_32x32x16_bf16 v[34:49], v[114:117], v[82:85], v[34:49]
	v_mfma_f32_32x32x16_bf16 v[50:65], v[106:109], v[86:89], v[50:65]
	ds_read_b128 v[66:69], v70 offset:9216
	ds_read_b128 v[126:129], v70 offset:9248
	ds_read_b128 v[130:133], v0 offset:9216
	ds_read_b128 v[122:125], v0 offset:9248
	ds_read_b128 v[118:121], v70 offset:9280
	ds_read_b128 v[110:113], v70 offset:9312
	ds_read_b128 v[114:117], v0 offset:9280
	ds_read_b128 v[106:109], v0 offset:9312
	s_waitcnt lgkmcnt(8)
	v_mfma_f32_32x32x16_bf16 v[34:49], v[194:197], v[86:89], v[34:49]
	v_add_u32_e32 v0, s44, v171
	v_cmp_le_u32_e64 s[0:1], v0, v136
	s_and_b64 s[0:1], vcc, s[0:1]
	v_add_u32_e32 v70, 2, v0
	v_cndmask_b32_e64 v50, v166, v50, s[0:1]
	v_cmp_lt_u32_e64 s[0:1], v0, v136
	s_and_b64 s[0:1], vcc, s[0:1]
	s_nop 0
	v_cndmask_b32_e64 v51, v166, v51, s[0:1]
	v_cmp_le_u32_e64 s[0:1], v70, v136
	s_and_b64 s[0:1], vcc, s[0:1]
	v_add_u32_e32 v70, 3, v0
	v_cndmask_b32_e64 v52, v166, v52, s[0:1]
	v_cmp_le_u32_e64 s[0:1], v70, v136
	s_and_b64 s[0:1], vcc, s[0:1]
	v_add_u32_e32 v70, 4, v0
	v_cndmask_b32_e64 v53, v166, v53, s[0:1]
	v_cmp_le_u32_e64 s[0:1], v70, v136
	s_and_b64 s[0:1], vcc, s[0:1]
	v_add_u32_e32 v70, 5, v0
	v_cndmask_b32_e64 v54, v166, v54, s[0:1]
	v_cmp_le_u32_e64 s[0:1], v70, v136
	s_and_b64 s[0:1], vcc, s[0:1]
	v_add_u32_e32 v70, 6, v0
	v_cndmask_b32_e64 v55, v166, v55, s[0:1]
	v_cmp_le_u32_e64 s[0:1], v70, v136
	v_add_u32_e32 v70, s44, v139
	s_and_b64 s[0:1], vcc, s[0:1]
	v_or_b32_e32 v71, 7, v70
	v_cndmask_b32_e64 v56, v166, v56, s[0:1]
	v_cmp_le_u32_e64 s[0:1], v71, v136
	s_and_b64 s[0:1], vcc, s[0:1]
	v_add_u32_e32 v71, 16, v0
	v_cndmask_b32_e64 v57, v166, v57, s[0:1]
	v_cmp_le_u32_e64 s[0:1], v71, v136
	s_and_b64 s[0:1], vcc, s[0:1]
	v_add_u32_e32 v71, 17, v0
	v_cndmask_b32_e64 v58, v166, v58, s[0:1]
	v_cmp_le_u32_e64 s[0:1], v71, v136
	s_and_b64 s[0:1], vcc, s[0:1]
	v_add_u32_e32 v71, 18, v0
	v_cndmask_b32_e64 v59, v166, v59, s[0:1]
	v_cmp_le_u32_e64 s[0:1], v71, v136
	s_and_b64 s[0:1], vcc, s[0:1]
	v_add_u32_e32 v71, 19, v0
	v_cndmask_b32_e64 v60, v166, v60, s[0:1]
	v_cmp_le_u32_e64 s[0:1], v71, v136
	s_and_b64 s[0:1], vcc, s[0:1]
	v_add_u32_e32 v71, 20, v0
	v_cndmask_b32_e64 v61, v166, v61, s[0:1]
	v_cmp_le_u32_e64 s[0:1], v71, v136
	s_and_b64 s[0:1], vcc, s[0:1]
	v_add_u32_e32 v71, 21, v0
	v_cndmask_b32_e64 v62, v166, v62, s[0:1]
	v_cmp_le_u32_e64 s[0:1], v71, v136
	s_and_b64 s[0:1], vcc, s[0:1]
	v_add_u32_e32 v71, 22, v0
	v_cndmask_b32_e64 v63, v166, v63, s[0:1]
	v_cmp_le_u32_e64 s[0:1], v71, v136
; DI float shx(float v, int m) { return __shfl_xor(v, m, 64); }
; template <int DQK, bool MASKED, int MODE, class MF>
; DI void attn_step(const bf16_t* sK, const bf16_t* sVt, const bf16x8 (&qf)[DQK / 16], f32x16& o0, f32x16& o1, float& m, float& l,
;                   float sc, const MF& mf, int lane, f32x16 (&s)[2], float invl, bool lanevalid = true) {
;     ...
; #pragma unroll
;   for (int sub = 0; sub < 2; ++sub)
; #pragma unroll
;     for (int q = 0; q < 16; ++q) {
;       if (MASKED) { const int kk = sub * 32 + 16 * (q >> 3) + 8 * h + (q & 7); s[sub][q] = mf(kk) ? s[sub][q] : -3.0e38f; }
;       if (MODE != 2) mxr = fmaxf(mxr, s[sub][q]);
;     }
;   float alpha = 1.f;
;   if (MODE != 2) {
;     float mx = fmaxf(m, mxr * sc);
;     mx = fmaxf(mx, shx(mx, 32));
	s_and_b64 s[0:1], vcc, s[0:1]
	v_or_b32_e32 v71, 23, v70
	v_cndmask_b32_e64 v64, v166, v64, s[0:1]
	v_cmp_le_u32_e64 s[0:1], v71, v136
	s_and_b64 s[0:1], vcc, s[0:1]
	v_add_u32_e32 v71, 32, v0
	v_cndmask_b32_e64 v65, v166, v65, s[0:1]
	v_cmp_le_u32_e64 s[0:1], v71, v136
	s_and_b64 s[0:1], vcc, s[0:1]
	v_add_u32_e32 v71, 33, v0
	v_cndmask_b32_e64 v34, v166, v34, s[0:1]
	v_cmp_le_u32_e64 s[0:1], v71, v136
	s_and_b64 s[0:1], vcc, s[0:1]
	v_add_u32_e32 v71, 34, v0
	v_cndmask_b32_e64 v35, v166, v35, s[0:1]
	v_cmp_le_u32_e64 s[0:1], v71, v136
	s_and_b64 s[0:1], vcc, s[0:1]
	v_add_u32_e32 v71, 35, v0
	v_cndmask_b32_e64 v36, v166, v36, s[0:1]
	v_cmp_le_u32_e64 s[0:1], v71, v136
	s_and_b64 s[0:1], vcc, s[0:1]
	v_add_u32_e32 v71, 36, v0
	v_cndmask_b32_e64 v37, v166, v37, s[0:1]
	v_cmp_le_u32_e64 s[0:1], v71, v136
	s_and_b64 s[0:1], vcc, s[0:1]
	v_add_u32_e32 v71, 37, v0
	v_cndmask_b32_e64 v38, v166, v38, s[0:1]
	v_cmp_le_u32_e64 s[0:1], v71, v136
	s_and_b64 s[0:1], vcc, s[0:1]
	v_add_u32_e32 v71, 38, v0
	v_cndmask_b32_e64 v39, v166, v39, s[0:1]
	v_cmp_le_u32_e64 s[0:1], v71, v136
	s_and_b64 s[0:1], vcc, s[0:1]
	v_or_b32_e32 v71, 39, v70
	v_cndmask_b32_e64 v40, v166, v40, s[0:1]
	v_cmp_le_u32_e64 s[0:1], v71, v136
	s_and_b64 s[0:1], vcc, s[0:1]
	v_add_u32_e32 v71, 48, v0
	v_cndmask_b32_e64 v41, v166, v41, s[0:1]
	v_cmp_le_u32_e64 s[0:1], v71, v136
	s_and_b64 s[0:1], vcc, s[0:1]
	v_add_u32_e32 v71, 49, v0
	v_cndmask_b32_e64 v42, v166, v42, s[0:1]
	v_cmp_le_u32_e64 s[0:1], v71, v136
	s_and_b64 s[0:1], vcc, s[0:1]
	s_nop 0
	v_cndmask_b32_e64 v189, v166, v43, s[0:1]
	v_add_u32_e32 v43, 50, v0
	v_cmp_le_u32_e64 s[0:1], v43, v136
	s_and_b64 s[0:1], vcc, s[0:1]
	v_add_u32_e32 v43, 51, v0
	v_cndmask_b32_e64 v190, v166, v44, s[0:1]
	v_cmp_le_u32_e64 s[0:1], v43, v136
	s_and_b64 s[0:1], vcc, s[0:1]
	v_add_u32_e32 v43, 52, v0
	v_cndmask_b32_e64 v191, v166, v45, s[0:1]
	v_cmp_le_u32_e64 s[0:1], v43, v136
	s_and_b64 s[0:1], vcc, s[0:1]
	v_add_u32_e32 v43, 53, v0
	v_cndmask_b32_e64 v194, v166, v46, s[0:1]
	v_cmp_le_u32_e64 s[0:1], v43, v136
	s_and_b64 s[0:1], vcc, s[0:1]
	v_add_u32_e32 v0, 54, v0
	v_cndmask_b32_e64 v195, v166, v47, s[0:1]
	v_cmp_le_u32_e64 s[0:1], v0, v136
	s_and_b64 s[0:1], vcc, s[0:1]
	v_or_b32_e32 v0, 55, v70
	v_cndmask_b32_e64 v196, v166, v48, s[0:1]
	v_cmp_le_u32_e64 s[0:1], v0, v136
	v_max3_f32 v0, v50, s8, v51
	v_max3_f32 v0, v0, v52, v53
	v_max3_f32 v0, v0, v54, v55
	v_max3_f32 v0, v0, v56, v57
	v_max3_f32 v0, v0, v58, v59
	v_max3_f32 v0, v0, v60, v61
	v_max3_f32 v0, v0, v62, v63
	v_max3_f32 v0, v0, v64, v65
	v_max3_f32 v0, v0, v34, v35
	v_max3_f32 v0, v0, v36, v37
	v_max3_f32 v0, v0, v38, v39
	v_max3_f32 v0, v0, v40, v41
	v_max3_f32 v0, v0, v42, v189
	s_and_b64 vcc, vcc, s[0:1]
	v_max3_f32 v0, v0, v190, v191
	v_cndmask_b32_e32 v197, v166, v49, vcc
	v_max3_f32 v0, v0, v194, v195
	v_max3_f32 v0, v0, v196, v197
	v_mul_f32_e32 v0, 0x3e38aa3b, v0
	v_max_f32_e32 v0, v188, v0
	ds_bpermute_b32 v43, v173, v0
	s_waitcnt lgkmcnt(0)
; #define MFMA(a, b, c) __builtin_amdgcn_mfma_f32_32x32x16_bf16((a), (b), (c), 0, 0, 0)
; DI unsigned pack2(float a, float b) { f32x2_t v = {a, b}; bf16x2_t r = __builtin_convertvector(v, bf16x2_t); return __builtin_bit_cast(unsigned, r); }
; DI float fexp2(float x) { return __builtin_amdgcn_exp2f(x); }
; DI float shx(float v, int m) { return __shfl_xor(v, m, 64); }
; template <int DQK, bool MASKED, int MODE, class MF>
; DI void attn_step(const bf16_t* sK, const bf16_t* sVt, const bf16x8 (&qf)[DQK / 16], f32x16& o0, f32x16& o1, float& m, float& l,
;                   float sc, const MF& mf, int lane, f32x16 (&s)[2], float invl, bool lanevalid = true) {
;     ...
;   float alpha = 1.f;
;   if (MODE != 2) {
;     float mx = fmaxf(m, mxr * sc);
;     mx = fmaxf(mx, shx(mx, 32));
;     if (!MASKED) mx = lanevalid ? mx : m;
;     alpha = fexp2(m - mx);
;     m = mx;
;   }
;   const float moff = (!MASKED && !lanevalid) ? 1.0e30f : m;
;   float ps = 0.f;
; #pragma unroll
;   for (int sub = 0; sub < 2; ++sub)
; #pragma unroll
;     for (int q = 0; q < 16; ++q) {
;       float pv = fexp2(__builtin_fmaf(s[sub][q], sc, -moff));
;       if (MASKED && MODE != 0) pv = (s[sub][q] > -1.0e38f) ? pv : 0.f;
;       if (MODE == 2) pv *= invl;
;       s[sub][q] = pv;
;       ps += pv;
;     }
;   if (MODE != 2) {
;     ps += shx(ps, 32);
;     l = l * alpha + ps;
;   }
;   if (MODE == 1) return;
;   if (MODE == 0) {
; #pragma unroll
;     for (int q = 0; q < 16; ++q) { o0[q] *= alpha; o1[q] *= alpha; }
;   }
; #pragma unroll
;   for (int sub = 0; sub < 2; ++sub)
; #pragma unroll
;     for (int s2 = 0; s2 < 2; ++s2) {
;       union { bf16x8 v; unsigned u[4]; } pb;
; #pragma unroll
;       for (int e = 0; e < 4; ++e) pb.u[e] = pack2(s[sub][8 * s2 + 2 * e], s[sub][8 * s2 + 2 * e + 1]);
;       o0 = MFMA(vf[sub][s2][0], pb.v, o0);
;       o1 = MFMA(vf[sub][s2][1], pb.v, o1);
;     }
	s_mov_b64 s[100:101], exec
	s_mov_b64 exec, 1
	ds_write_b32 v252, v254
	s_mov_b64 exec, s[100:101]
	v_max_f32_e32 v43, v43, v43
	v_max_f32_e32 v0, v0, v43
	v_fma_f32 v43, v50, s33, -v0
	v_exp_f32_e32 v50, v43
	v_fma_f32 v43, v51, s33, -v0
	v_exp_f32_e32 v51, v43
	v_fma_f32 v43, v52, s33, -v0
	v_exp_f32_e32 v70, v43
	v_fma_f32 v45, v53, s33, -v0
	v_exp_f32_e32 v53, v45
	v_fma_f32 v45, v54, s33, -v0
	v_add_f32_e32 v44, 0, v50
	v_exp_f32_e32 v54, v45
	v_fma_f32 v45, v55, s33, -v0
	v_add_f32_e32 v44, v51, v44
	v_exp_f32_e32 v55, v45
	v_fma_f32 v45, v56, s33, -v0
	v_add_f32_e32 v44, v70, v44
	v_exp_f32_e32 v56, v45
	v_fma_f32 v45, v57, s33, -v0
	v_add_f32_e32 v44, v53, v44
	v_exp_f32_e32 v57, v45
	v_fma_f32 v45, v58, s33, -v0
	v_sub_f32_e32 v43, v141, v0
	v_add_f32_e32 v44, v54, v44
	v_exp_f32_e32 v141, v45
	v_fma_f32 v45, v59, s33, -v0
	v_add_f32_e32 v44, v55, v44
	v_exp_f32_e32 v188, v45
	v_fma_f32 v45, v60, s33, -v0
	v_add_f32_e32 v44, v56, v44
	v_exp_f32_e32 v198, v45
	v_fma_f32 v45, v61, s33, -v0
	v_add_f32_e32 v44, v57, v44
	v_exp_f32_e32 v199, v45
	v_fma_f32 v45, v62, s33, -v0
	v_add_f32_e32 v44, v141, v44
	v_exp_f32_e32 v200, v45
	v_fma_f32 v45, v63, s33, -v0
	v_add_f32_e32 v44, v188, v44
	v_exp_f32_e32 v201, v45
	v_fma_f32 v45, v64, s33, -v0
	v_add_f32_e32 v44, v198, v44
	v_exp_f32_e32 v202, v45
	v_fma_f32 v45, v65, s33, -v0
	v_add_f32_e32 v44, v199, v44
	v_exp_f32_e32 v203, v45
	v_fma_f32 v34, v34, s33, -v0
	v_add_f32_e32 v44, v200, v44
	v_exp_f32_e32 v204, v34
	v_fma_f32 v34, v35, s33, -v0
	v_add_f32_e32 v44, v201, v44
	v_exp_f32_e32 v205, v34
	v_fma_f32 v34, v36, s33, -v0
	v_add_f32_e32 v44, v202, v44
	v_exp_f32_e32 v206, v34
	v_fma_f32 v35, v37, s33, -v0
	v_add_f32_e32 v34, v203, v44
	v_exp_f32_e32 v207, v35
	v_fma_f32 v35, v38, s33, -v0
	v_add_f32_e32 v34, v204, v34
	v_exp_f32_e32 v208, v35
	v_fma_f32 v35, v39, s33, -v0
	v_add_f32_e32 v34, v205, v34
	v_exp_f32_e32 v209, v35
	v_fma_f32 v35, v40, s33, -v0
	v_add_f32_e32 v34, v206, v34
	v_exp_f32_e32 v210, v35
	v_add_f32_e32 v34, v207, v34
	v_add_f32_e32 v34, v208, v34
	v_exp_f32_e32 v52, v43
	v_add_f32_e32 v34, v209, v34
	v_add_f32_e32 v211, v210, v34
	v_fma_f32 v34, v41, s33, -v0
	v_exp_f32_e32 v212, v34
	v_fma_f32 v34, v42, s33, -v0
	v_exp_f32_e32 v213, v34
	v_pk_mul_f32 v[48:49], v[32:33], v[52:53] op_sel_hi:[1,0]
	v_pk_mul_f32 v[46:47], v[30:31], v[52:53] op_sel_hi:[1,0]
	v_pk_mul_f32 v[44:45], v[28:29], v[52:53] op_sel_hi:[1,0]
	v_pk_mul_f32 v[42:43], v[26:27], v[52:53] op_sel_hi:[1,0]
	v_pk_mul_f32 v[40:41], v[24:25], v[52:53] op_sel_hi:[1,0]
	v_pk_mul_f32 v[38:39], v[22:23], v[52:53] op_sel_hi:[1,0]
	v_pk_mul_f32 v[36:37], v[20:21], v[52:53] op_sel_hi:[1,0]
	v_pk_mul_f32 v[34:35], v[18:19], v[52:53] op_sel_hi:[1,0]
	v_pk_mul_f32 v[72:73], v[16:17], v[52:53] op_sel_hi:[1,0]
	v_cvt_pk_bf16_f32 v16, v50, v51
	v_cvt_pk_bf16_f32 v17, v70, v53
	v_cvt_pk_bf16_f32 v18, v54, v55
	v_cvt_pk_bf16_f32 v19, v56, v57
	v_pk_mul_f32 v[70:71], v[14:15], v[52:53] op_sel_hi:[1,0]
	v_pk_mul_f32 v[64:65], v[8:9], v[52:53] op_sel_hi:[1,0]
	v_mfma_f32_32x32x16_bf16 v[34:49], v[66:69], v[16:19], v[34:49]
	v_mul_f32_e64 v68, v12, v52
	v_mul_f32_e64 v69, v13, v52
	v_mul_f32_e64 v66, v10, v52
	v_mul_f32_e64 v67, v11, v52
	v_mul_f32_e64 v62, v6, v52
	v_mul_f32_e64 v63, v7, v52
	v_pk_mul_f32 v[60:61], v[4:5], v[52:53] op_sel_hi:[1,0]
	v_pk_mul_f32 v[58:59], v[2:3], v[52:53] op_sel_hi:[1,0]
	v_add_f32_e32 v2, v212, v211
	v_add_f32_e32 v6, v213, v2
	v_mfma_f32_32x32x16_bf16 v[58:73], v[130:133], v[16:19], v[58:73]
	v_cvt_pk_bf16_f32 v2, v141, v188
	v_cvt_pk_bf16_f32 v3, v198, v199
	v_cvt_pk_bf16_f32 v4, v200, v201
	v_cvt_pk_bf16_f32 v5, v202, v203
	v_fma_f32 v7, v189, s33, -v0
	v_exp_f32_e32 v7, v7
	v_fma_f32 v8, v190, s33, -v0
	v_mfma_f32_32x32x16_bf16 v[34:49], v[126:129], v[2:5], v[34:49]
	v_exp_f32_e32 v8, v8
	v_fma_f32 v9, v191, s33, -v0
	v_exp_f32_e32 v9, v9
	v_fma_f32 v11, v195, s33, -v0
	v_add_f32_e32 v6, v7, v6
	v_exp_f32_e32 v11, v11
	v_fma_f32 v12, v196, s33, -v0
	v_mfma_f32_32x32x16_bf16 v[58:73], v[122:125], v[2:5], v[58:73]
	v_fma_f32 v2, v194, s33, -v0
	v_exp_f32_e32 v10, v2
	v_cvt_pk_bf16_f32 v2, v204, v205
	v_cvt_pk_bf16_f32 v3, v206, v207
	v_cvt_pk_bf16_f32 v4, v208, v209
	v_cvt_pk_bf16_f32 v5, v210, v212
	v_add_f32_e32 v6, v8, v6
	v_exp_f32_e32 v12, v12
	v_mfma_f32_32x32x16_bf16 v[34:49], v[118:121], v[2:5], v[34:49]
	v_fma_f32 v13, v197, s33, -v0
	v_add_f32_e32 v6, v9, v6
	v_exp_f32_e32 v13, v13
	v_add_f32_e32 v6, v10, v6
	v_mfma_f32_32x32x16_bf16 v[58:73], v[114:117], v[2:5], v[58:73]
	v_add_f32_e32 v2, v11, v6
	v_add_f32_e32 v2, v12, v2
	v_add_f32_e32 v6, v13, v2
	v_cvt_pk_bf16_f32 v2, v213, v7
	v_cvt_pk_bf16_f32 v3, v8, v9
	v_cvt_pk_bf16_f32 v4, v10, v11
	v_cvt_pk_bf16_f32 v5, v12, v13
	s_nop 1
	v_mfma_f32_32x32x16_bf16 v[34:49], v[110:113], v[2:5], v[34:49]
	v_mfma_f32_32x32x16_bf16 v[58:73], v[106:109], v[2:5], v[58:73]
	v_fma_f32 v50, v185, v52, v6

; DI void phase_attn_nsa(const Params& P, bf16_t* og, unsigned char* smem, int L, int G) {
;     ...
;       tot_addto(totL, tid, o0, o1, g1 / l);
;       tot_store(totL, tid, o0, o1, 1.f);
;     }
;     {
;       const bf16_t* kb = big + NS_KW + (size_t)b * SEQ * 256 + g * 64;
;       const bf16_t* vb = big + NS_VWT + (size_t)((b * 4 + g) * 64) * SEQ;
;       float m = NEGF, l = 0.f; o_zero(o0, o1);
;       const int jlo = (t0 - 511 > 0 ? t0 - 511 : 0) >> 6, jhi = (t0 + 31) >> 6;
;       KVR R; kv64_fetch(R, kb, 256, vb, SEQ, jlo * 64, true, tid);
;       __syncthreads();
;       kv64_store(R, sK, sVt, tid);
;       if (jlo < jhi) kv64_fetch(R, kb, 256, vb, SEQ, jlo * 64 + 64, true, tid);
.LBB0_1357:
	ds_bpermute_b32 v247, v173, v185
	s_waitcnt lgkmcnt(0)
	v_add_f32_e32 v185, v185, v247
	v_readlane_b32 s0, v246, 48
	v_readlane_b32 s1, v246, 49
	v_lshlrev_b32_e32 v0, 1, v187
	v_mov_b32_e32 v141, v1
	v_lshl_add_u64 v[34:35], v[144:145], 1, s[0:1]
	v_readlane_b32 s0, v246, 50
	v_readlane_b32 s1, v246, 51
	v_lshl_add_u64 v[34:35], v[34:35], 0, v[0:1]
	v_div_scale_f32 v72, vcc, v178, v185, v178
	v_lshl_add_u64 v[38:39], v[142:143], 1, s[0:1]
	s_max_i32 s0, s46, 0x1ff
	s_add_i32 s2, s0, 0xfffffe01
	s_and_b32 s44, s2, 0xffffffc0
	v_or_b32_e32 v0, s44, v169
	v_lshlrev_b64 v[36:37], 9, v[0:1]
	v_or_b32_e32 v0, s44, v174
	v_lshl_add_u64 v[36:37], v[34:35], 0, v[36:37]
	v_lshlrev_b64 v[40:41], 9, v[0:1]
	v_lshl_add_u64 v[36:37], v[36:37], 0, v[140:141]
	v_lshl_add_u64 v[40:41], v[34:35], 0, v[40:41]
	v_lshlrev_b32_e32 v0, 1, v186
	v_lshl_add_u64 v[40:41], v[40:41], 0, v[140:141]
	global_load_dwordx4 v[42:45], v[36:37], off
	global_load_dwordx4 v[46:49], v[40:41], off
	v_lshl_add_u64 v[36:37], v[38:39], 0, v[0:1]
	v_lshlrev_b32_e32 v0, 1, v184
	s_lshl_b64 s[0:1], s[44:45], 1
	v_lshl_add_u64 v[38:39], v[38:39], 0, v[0:1]
	v_lshl_add_u64 v[40:41], v[36:37], 0, s[0:1]
	v_lshl_add_u64 v[54:55], v[38:39], 0, s[0:1]
	v_lshl_add_u64 v[40:41], v[40:41], 0, v[140:141]
	v_lshl_add_u64 v[58:59], v[54:55], 0, v[140:141]
	global_load_dwordx4 v[50:53], v[40:41], off
	global_load_dwordx4 v[54:57], v[58:59], off
	v_div_scale_f32 v0, s[0:1], v185, v185, v178
	v_rcp_f32_e32 v73, v0
	ds_read_b128 v[60:63], v180 offset:37376
	ds_read_b128 v[64:67], v180 offset:41472
	ds_read_b128 v[68:71], v180 offset:53760
	s_waitcnt vmcnt(7)
	ds_read_b128 v[90:93], v180 offset:57856
	s_waitcnt vmcnt(6)
	ds_read_b128 v[94:97], v180 offset:45568
	s_waitcnt vmcnt(5)
	ds_read_b128 v[98:101], v180 offset:49664
	s_waitcnt vmcnt(4)
	ds_read_b128 v[102:105], v180 offset:61952
	ds_read_b128 v[106:109], v181 offset:28672
	s_lshr_b32 s2, s2, 6
	v_fma_f32 v110, -v0, v73, 1.0
	v_fmac_f32_e32 v73, v110, v73
	v_mul_f32_e32 v110, v72, v73
	v_fma_f32 v111, -v0, v110, v72
	v_fmac_f32_e32 v110, v111, v73
	v_fma_f32 v0, -v0, v110, v72
	v_div_fmas_f32 v0, v0, v73, v110
	v_div_fixup_f32 v0, v0, v185, v178
	s_waitcnt lgkmcnt(7)
	v_pk_fma_f32 v[18:19], v[0:1], v[18:19], v[60:61] op_sel_hi:[0,1,1]
	v_pk_fma_f32 v[20:21], v[0:1], v[20:21], v[62:63] op_sel_hi:[0,1,1]
	s_cmp_lt_u32 s2, s20
	s_waitcnt lgkmcnt(5)
	v_pk_fma_f32 v[2:3], v[0:1], v[2:3], v[68:69] op_sel_hi:[0,1,1]
	v_pk_fma_f32 v[4:5], v[0:1], v[4:5], v[70:71] op_sel_hi:[0,1,1]
	v_pk_fma_f32 v[22:23], v[0:1], v[22:23], v[64:65] op_sel_hi:[0,1,1]
	v_pk_fma_f32 v[24:25], v[0:1], v[24:25], v[66:67] op_sel_hi:[0,1,1]
	s_waitcnt lgkmcnt(4)
	v_pk_fma_f32 v[6:7], v[0:1], v[6:7], v[90:91] op_sel_hi:[0,1,1]
	v_pk_fma_f32 v[8:9], v[0:1], v[8:9], v[92:93] op_sel_hi:[0,1,1]
	s_waitcnt lgkmcnt(3)
	v_pk_fma_f32 v[26:27], v[0:1], v[26:27], v[94:95] op_sel_hi:[0,1,1]
	v_pk_fma_f32 v[28:29], v[0:1], v[28:29], v[96:97] op_sel_hi:[0,1,1]
	s_waitcnt lgkmcnt(1)
	v_pk_fma_f32 v[10:11], v[0:1], v[10:11], v[102:103] op_sel_hi:[0,1,1]
	v_pk_fma_f32 v[12:13], v[0:1], v[12:13], v[104:105] op_sel_hi:[0,1,1]
	v_pk_fma_f32 v[30:31], v[0:1], v[30:31], v[98:99] op_sel_hi:[0,1,1]
	v_pk_fma_f32 v[32:33], v[0:1], v[32:33], v[100:101] op_sel_hi:[0,1,1]
	s_waitcnt lgkmcnt(0)
	v_pk_fma_f32 v[14:15], v[0:1], v[14:15], v[106:107] op_sel_hi:[0,1,1]
	v_pk_fma_f32 v[16:17], v[0:1], v[16:17], v[108:109] op_sel_hi:[0,1,1]
	ds_write_b128 v180, v[18:21] offset:37376
	ds_write_b128 v180, v[2:5] offset:53760
	ds_write_b128 v180, v[22:25] offset:41472
	ds_write_b128 v180, v[6:9] offset:57856
	ds_write_b128 v180, v[26:29] offset:45568
	ds_write_b128 v180, v[10:13] offset:61952
	ds_write_b128 v180, v[30:33] offset:49664
	ds_write_b128 v181, v[14:17] offset:28672
	s_waitcnt lgkmcnt(0)
	v_lshrrev_b32_e32 v250, 8, v192
	v_bfe_u32 v252, v192, 6, 2
	v_and_b32_e32 v251, 7, v192
	v_lshlrev_b32_e32 v250, 6, v250
	v_lshl_add_u32 v252, v252, 2, v250
	v_lshl_add_u32 v250, v251, 2, v250
	v_add_u32_e32 v252, 0x24800, v252
	v_add_u32_e32 v250, 0x24800, v250
	v_mov_b32_e32 v254, 0
	s_mov_b32 s99, 0
	s_barrier
	s_mov_b64 s[100:101], exec
	s_mov_b64 exec, 1
	ds_write_b32 v252, v254
	ds_write_b32 v252, v254 offset:16
	s_mov_b64 exec, s[100:101]
	s_waitcnt vmcnt(3)
	ds_write_b128 v170, v[42:45]
	s_waitcnt vmcnt(2)
	ds_write_b128 v170, v[46:49] offset:4608
	s_waitcnt vmcnt(1)
	ds_write_b128 v170, v[50:53] offset:9216
	s_waitcnt vmcnt(0)
	ds_write_b128 v170, v[54:57] offset:13824
	s_cbranch_scc0 .LBB0_1359
	s_add_i32 s0, s44, 64
	v_or_b32_e32 v0, s0, v169
	v_lshlrev_b64 v[2:3], 9, v[0:1]
	v_or_b32_e32 v0, s0, v174
	v_lshl_add_u64 v[2:3], v[34:35], 0, v[2:3]
	v_lshlrev_b64 v[4:5], 9, v[0:1]
	v_lshl_add_u64 v[2:3], v[2:3], 0, v[140:141]
	v_lshl_add_u64 v[4:5], v[34:35], 0, v[4:5]
	v_lshl_add_u64 v[4:5], v[4:5], 0, v[140:141]
	global_load_dwordx4 v[42:45], v[2:3], off
	global_load_dwordx4 v[46:49], v[4:5], off
	global_load_dwordx4 v[50:53], v[40:41], off offset:128
	global_load_dwordx4 v[54:57], v[58:59], off offset:128

; DI void phase_attn_nsa(const Params& P, bf16_t* og, unsigned char* smem, int L, int G) {
;     ...
;       for (int j = jlo; j <= jhi; ++j) {
;         const int key0 = j * 64, cb = (j - jlo) & 1;
;         __syncthreads();
;         if (j < jhi) kv64_store(R, sK + (cb ^ 1) * KVB64, sVt + (cb ^ 1) * KVB64, tid);
.LBB0_1361:
	s_add_i32 s0, s2, s4
	s_and_b32 s5, s4, 1
	s_add_i32 s98, s4, 1
	v_mov_b32_e32 v254, s98
	s_cmp_eq_u32 s4, 0
	s_cbranch_scc0 .Lmy_nsawin_spin
	s_waitcnt lgkmcnt(0)
	s_barrier
	s_branch .Lmy_nsawin_go

; #define MFMA(a, b, c) __builtin_amdgcn_mfma_f32_32x32x16_bf16((a), (b), (c), 0, 0, 0)
; template <int DQK, bool MASKED, int MODE, class MF>
; DI void attn_step(const bf16_t* sK, const bf16_t* sVt, const bf16x8 (&qf)[DQK / 16], f32x16& o0, f32x16& o1, float& m, float& l,
;                   float sc, const MF& mf, int lane, f32x16 (&s)[2], float invl, bool lanevalid = true) {
;     ...
;   bf16x8 kf[2][DQK / 16];
; #pragma unroll
;   for (int sub = 0; sub < 2; ++sub)
; #pragma unroll
;     for (int ks = 0; ks < DQK / 16; ++ks) kf[sub][ks] = *(const bf16x8*)(sK + (sub * 32 + pr) * KST + ks * 16 + 8 * h);
;   __builtin_amdgcn_sched_barrier(0);
; #pragma unroll
;   for (int q = 0; q < 16; ++q) { s[0][q] = 0.f; s[1][q] = 0.f; }
; #pragma unroll
;   for (int ks = 0; ks < DQK / 16; ++ks) {
;     s[0] = MFMA(kf[0][ks], qf[ks], s[0]);
;     s[1] = MFMA(kf[1][ks], qf[ks], s[1]);
;   }
;   bf16x8 vf[2][2][2];
;   if (MODE != 1) {
; #pragma unroll
;     for (int sub = 0; sub < 2; ++sub)
; #pragma unroll
;       for (int s2 = 0; s2 < 2; ++s2) {
;         vf[sub][s2][0] = *(const bf16x8*)(sVt + r * 72 + sub * 32 + s2 * 16 + 8 * h);
;         vf[sub][s2][1] = *(const bf16x8*)(sVt + (32 + r) * 72 + sub * 32 + s2 * 16 + 8 * h);
;       }
;     __builtin_amdgcn_sched_barrier(0);
;   }
;   float mxr = -3.0e38f;
; #pragma unroll
;   for (int sub = 0; sub < 2; ++sub)
; #pragma unroll
;     for (int q = 0; q < 16; ++q) {
;       if (MASKED) { const int kk = sub * 32 + 16 * (q >> 3) + 8 * h + (q & 7); s[sub][q] = mf(kk) ? s[sub][q] : -3.0e38f; }
; DI void phase_attn_nsa(const Params& P, bf16_t* og, unsigned char* smem, int L, int G) {
;     ...
;         auto mf = [&](int kk) { const int key = key0 + kk; return key <= t && key > t - 512; };
;         if (key0 + 63 > t0 || key0 <= t0 + 31 - 512) attn_step<64, true, 0>(sK + cb * KVB64, sVt + cb * KVB64, qf, o0, o1, m, l, sc, mf, lane, s, 0.f);
;         else attn_step<64, false, 0>(sK + cb * KVB64, sVt + cb * KVB64, qf, o0, o1, m, l, sc, mf, lane, s, 0.f);
.LBB0_1365:
	s_add_i32 s0, s44, 63
	s_cmp_le_u32 s0, s46
	s_cselect_b64 s[0:1], -1, 0
	s_cmp_gt_i32 s44, s3
	s_cselect_b64 s[6:7], -1, 0
	s_and_b64 s[6:7], s[0:1], s[6:7]
	s_mulk_i32 s5, 0x2400
	v_lshl_add_u32 v98, s5, 1, v153
	s_mov_b64 s[0:1], -1
	s_and_b64 vcc, exec, s[6:7]
	v_max_f32_e32 v149, v148, v148
	s_cbranch_vccnz .LBB0_1367
	v_lshl_add_u32 v0, s5, 1, v172
	ds_read_b128 v[2:5], v0
	ds_read_b128 v[34:37], v0 offset:32
	ds_read_b128 v[38:41], v0 offset:64
	ds_read_b128 v[58:61], v0 offset:96
	ds_read_b128 v[6:9], v0 offset:4608
	ds_read_b128 v[62:65], v0 offset:4640
	ds_read_b128 v[66:69], v0 offset:4672
	ds_read_b128 v[184:187], v0 offset:4704
	s_waitcnt lgkmcnt(7)
	v_mfma_f32_32x32x16_bf16 v[18:33], v[2:5], v[74:77], 0
	v_lshlrev_b32_e32 v0, 1, v171
	s_waitcnt lgkmcnt(3)
	v_mfma_f32_32x32x16_bf16 v[2:17], v[6:9], v[74:77], 0
	v_mfma_f32_32x32x16_bf16 v[18:33], v[34:37], v[78:81], v[18:33]
	v_add3_u32 v34, v98, v175, v0
	v_add3_u32 v0, v98, v177, v0
	s_waitcnt lgkmcnt(2)
	v_mfma_f32_32x32x16_bf16 v[2:17], v[62:65], v[78:81], v[2:17]
	v_mfma_f32_32x32x16_bf16 v[18:33], v[38:41], v[82:85], v[18:33]
	s_waitcnt lgkmcnt(1)
	v_mfma_f32_32x32x16_bf16 v[2:17], v[66:69], v[82:85], v[2:17]
	v_mfma_f32_32x32x16_bf16 v[18:33], v[58:61], v[86:89], v[18:33]
	ds_read_b128 v[94:97], v34 offset:9216
	ds_read_b128 v[70:73], v34 offset:9248
	ds_read_b128 v[90:93], v0 offset:9216
	ds_read_b128 v[66:69], v0 offset:9248
	ds_read_b128 v[62:65], v34 offset:9280
	ds_read_b128 v[38:41], v34 offset:9312
	ds_read_b128 v[58:61], v0 offset:9280
	ds_read_b128 v[34:37], v0 offset:9312
	s_waitcnt lgkmcnt(8)
	v_mfma_f32_32x32x16_bf16 v[2:17], v[184:187], v[86:89], v[2:17]
	v_add_u32_e32 v0, s44, v171
	v_cmp_le_u32_e32 vcc, v0, v136
	v_cmp_gt_i32_e64 s[0:1], v0, v146
	s_and_b64 vcc, vcc, s[0:1]
	v_cndmask_b32_e32 v18, v166, v18, vcc
	v_cmp_lt_u32_e32 vcc, v0, v136
	v_cmp_ge_i32_e64 s[0:1], v0, v146
	s_and_b64 vcc, vcc, s[0:1]
	v_add_u32_e32 v99, 2, v0
	v_cndmask_b32_e32 v19, v166, v19, vcc
	v_cmp_le_u32_e32 vcc, v99, v136
	v_cmp_gt_i32_e64 s[0:1], v99, v146
	s_and_b64 vcc, vcc, s[0:1]
	v_add_u32_e32 v99, 3, v0
	v_cndmask_b32_e32 v20, v166, v20, vcc
	v_cmp_le_u32_e32 vcc, v99, v136
	v_cmp_gt_i32_e64 s[0:1], v99, v146
	s_and_b64 vcc, vcc, s[0:1]
	v_add_u32_e32 v99, 4, v0
	v_cndmask_b32_e32 v21, v166, v21, vcc
	v_cmp_le_u32_e32 vcc, v99, v136
	v_cmp_gt_i32_e64 s[0:1], v99, v146
	s_and_b64 vcc, vcc, s[0:1]
	v_add_u32_e32 v99, 5, v0
	v_cndmask_b32_e32 v22, v166, v22, vcc
	v_cmp_le_u32_e32 vcc, v99, v136
	v_cmp_gt_i32_e64 s[0:1], v99, v146
	s_and_b64 vcc, vcc, s[0:1]
	v_add_u32_e32 v99, 6, v0
	v_cndmask_b32_e32 v23, v166, v23, vcc
	v_cmp_le_u32_e32 vcc, v99, v136
	v_cmp_gt_i32_e64 s[0:1], v99, v146
	v_add_u32_e32 v99, s44, v139
	s_and_b64 vcc, vcc, s[0:1]
	v_or_b32_e32 v100, 7, v99
	v_cndmask_b32_e32 v24, v166, v24, vcc
	v_cmp_le_u32_e32 vcc, v100, v136
	v_cmp_gt_i32_e64 s[0:1], v100, v146
	s_and_b64 vcc, vcc, s[0:1]
	v_add_u32_e32 v100, 16, v0
	v_cndmask_b32_e32 v25, v166, v25, vcc
	v_cmp_le_u32_e32 vcc, v100, v136
	v_cmp_gt_i32_e64 s[0:1], v100, v146
	s_and_b64 vcc, vcc, s[0:1]
	v_add_u32_e32 v100, 17, v0
	v_cndmask_b32_e32 v26, v166, v26, vcc
	v_cmp_le_u32_e32 vcc, v100, v136
	v_cmp_gt_i32_e64 s[0:1], v100, v146
	s_and_b64 vcc, vcc, s[0:1]
	v_add_u32_e32 v100, 18, v0
	v_cndmask_b32_e32 v27, v166, v27, vcc
	v_cmp_le_u32_e32 vcc, v100, v136
	v_cmp_gt_i32_e64 s[0:1], v100, v146
	s_and_b64 vcc, vcc, s[0:1]
	v_add_u32_e32 v100, 19, v0
	v_cndmask_b32_e32 v28, v166, v28, vcc
	v_cmp_le_u32_e32 vcc, v100, v136
	v_cmp_gt_i32_e64 s[0:1], v100, v146
	s_and_b64 vcc, vcc, s[0:1]
	v_add_u32_e32 v100, 20, v0
	v_cndmask_b32_e32 v29, v166, v29, vcc
	v_cmp_le_u32_e32 vcc, v100, v136
	v_cmp_gt_i32_e64 s[0:1], v100, v146
	s_and_b64 vcc, vcc, s[0:1]
	v_add_u32_e32 v100, 21, v0
	v_cndmask_b32_e32 v30, v166, v30, vcc
	v_cmp_le_u32_e32 vcc, v100, v136
	v_cmp_gt_i32_e64 s[0:1], v100, v146
	s_and_b64 vcc, vcc, s[0:1]
	v_add_u32_e32 v100, 22, v0
	v_cndmask_b32_e32 v31, v166, v31, vcc
	v_cmp_le_u32_e32 vcc, v100, v136
	v_cmp_gt_i32_e64 s[0:1], v100, v146
	s_and_b64 vcc, vcc, s[0:1]
	v_or_b32_e32 v100, 23, v99
	v_cndmask_b32_e32 v32, v166, v32, vcc
	v_cmp_le_u32_e32 vcc, v100, v136
	v_cmp_gt_i32_e64 s[0:1], v100, v146
	s_and_b64 vcc, vcc, s[0:1]
	v_add_u32_e32 v100, 32, v0
	v_cndmask_b32_e32 v33, v166, v33, vcc
	v_cmp_le_u32_e32 vcc, v100, v136
	v_cmp_gt_i32_e64 s[0:1], v100, v146
	s_and_b64 vcc, vcc, s[0:1]
	v_add_u32_e32 v100, 33, v0
	v_cndmask_b32_e32 v2, v166, v2, vcc
	v_cmp_le_u32_e32 vcc, v100, v136
	v_cmp_gt_i32_e64 s[0:1], v100, v146
	s_and_b64 vcc, vcc, s[0:1]
	v_add_u32_e32 v100, 34, v0
	v_cndmask_b32_e32 v3, v166, v3, vcc
	v_cmp_le_u32_e32 vcc, v100, v136
	v_cmp_gt_i32_e64 s[0:1], v100, v146
	s_and_b64 vcc, vcc, s[0:1]
	v_add_u32_e32 v100, 35, v0
	v_cndmask_b32_e32 v4, v166, v4, vcc
	v_cmp_le_u32_e32 vcc, v100, v136
	v_cmp_gt_i32_e64 s[0:1], v100, v146
	s_and_b64 vcc, vcc, s[0:1]
	v_add_u32_e32 v100, 36, v0
	v_cndmask_b32_e32 v5, v166, v5, vcc
	v_cmp_le_u32_e32 vcc, v100, v136
	v_cmp_gt_i32_e64 s[0:1], v100, v146
	s_and_b64 vcc, vcc, s[0:1]
	v_add_u32_e32 v100, 37, v0
	v_cndmask_b32_e32 v6, v166, v6, vcc
	v_cmp_le_u32_e32 vcc, v100, v136
	v_cmp_gt_i32_e64 s[0:1], v100, v146
	s_and_b64 vcc, vcc, s[0:1]
	v_add_u32_e32 v100, 38, v0
	v_cndmask_b32_e32 v7, v166, v7, vcc
	v_cmp_le_u32_e32 vcc, v100, v136
	v_cmp_gt_i32_e64 s[0:1], v100, v146
	s_and_b64 vcc, vcc, s[0:1]
	v_or_b32_e32 v100, 39, v99
	v_cndmask_b32_e32 v8, v166, v8, vcc
	v_cmp_le_u32_e32 vcc, v100, v136
	v_cmp_gt_i32_e64 s[0:1], v100, v146
	s_and_b64 vcc, vcc, s[0:1]
	v_add_u32_e32 v100, 48, v0
	v_cndmask_b32_e32 v9, v166, v9, vcc
; #define MFMA(a, b, c) __builtin_amdgcn_mfma_f32_32x32x16_bf16((a), (b), (c), 0, 0, 0)
; DI unsigned pack2(float a, float b) { f32x2_t v = {a, b}; bf16x2_t r = __builtin_convertvector(v, bf16x2_t); return __builtin_bit_cast(unsigned, r); }
; DI float fexp2(float x) { return __builtin_amdgcn_exp2f(x); }
; DI float shx(float v, int m) { return __shfl_xor(v, m, 64); }
; template <int DQK, bool MASKED, int MODE, class MF>
; DI void attn_step(const bf16_t* sK, const bf16_t* sVt, const bf16x8 (&qf)[DQK / 16], f32x16& o0, f32x16& o1, float& m, float& l,
;                   float sc, const MF& mf, int lane, f32x16 (&s)[2], float invl, bool lanevalid = true) {
;     ...
;       if (MASKED) { const int kk = sub * 32 + 16 * (q >> 3) + 8 * h + (q & 7); s[sub][q] = mf(kk) ? s[sub][q] : -3.0e38f; }
;       if (MODE != 2) mxr = fmaxf(mxr, s[sub][q]);
;     }
;   float alpha = 1.f;
;   if (MODE != 2) {
;     float mx = fmaxf(m, mxr * sc);
;     mx = fmaxf(mx, shx(mx, 32));
;     if (!MASKED) mx = lanevalid ? mx : m;
;     alpha = fexp2(m - mx);
;     m = mx;
;   }
;   const float moff = (!MASKED && !lanevalid) ? 1.0e30f : m;
;   float ps = 0.f;
; #pragma unroll
;   for (int sub = 0; sub < 2; ++sub)
; #pragma unroll
;     for (int q = 0; q < 16; ++q) {
;       float pv = fexp2(__builtin_fmaf(s[sub][q], sc, -moff));
;       if (MASKED && MODE != 0) pv = (s[sub][q] > -1.0e38f) ? pv : 0.f;
;       if (MODE == 2) pv *= invl;
;       s[sub][q] = pv;
;       ps += pv;
;     }
;   if (MODE != 2) {
;     ps += shx(ps, 32);
;     l = l * alpha + ps;
;   }
;   if (MODE == 1) return;
;   if (MODE == 0) {
; #pragma unroll
;     for (int q = 0; q < 16; ++q) { o0[q] *= alpha; o1[q] *= alpha; }
;   }
; #pragma unroll
;   for (int sub = 0; sub < 2; ++sub)
; #pragma unroll
;     for (int s2 = 0; s2 < 2; ++s2) {
;       union { bf16x8 v; unsigned u[4]; } pb;
; #pragma unroll
;       for (int e = 0; e < 4; ++e) pb.u[e] = pack2(s[sub][8 * s2 + 2 * e], s[sub][8 * s2 + 2 * e + 1]);
;       o0 = MFMA(vf[sub][s2][0], pb.v, o0);
;       o1 = MFMA(vf[sub][s2][1], pb.v, o1);
;     }
	v_cmp_le_u32_e32 vcc, v100, v136
	v_cmp_gt_i32_e64 s[0:1], v100, v146
	s_and_b64 vcc, vcc, s[0:1]
	v_add_u32_e32 v100, 49, v0
	v_cndmask_b32_e32 v10, v166, v10, vcc
	v_cmp_le_u32_e32 vcc, v100, v136
	v_cmp_gt_i32_e64 s[0:1], v100, v146
	s_and_b64 vcc, vcc, s[0:1]
	v_cndmask_b32_e32 v101, v166, v11, vcc
	v_add_u32_e32 v11, 50, v0
	v_cmp_le_u32_e32 vcc, v11, v136
	v_cmp_gt_i32_e64 s[0:1], v11, v146
	s_and_b64 vcc, vcc, s[0:1]
	v_add_u32_e32 v11, 51, v0
	v_cndmask_b32_e32 v150, v166, v12, vcc
	v_cmp_le_u32_e32 vcc, v11, v136
	v_cmp_gt_i32_e64 s[0:1], v11, v146
	s_and_b64 vcc, vcc, s[0:1]
	v_add_u32_e32 v11, 52, v0
	v_cndmask_b32_e32 v151, v166, v13, vcc
	v_cmp_le_u32_e32 vcc, v11, v136
	v_cmp_gt_i32_e64 s[0:1], v11, v146
	s_and_b64 vcc, vcc, s[0:1]
	v_add_u32_e32 v11, 53, v0
	v_cndmask_b32_e32 v174, v166, v14, vcc
	v_cmp_le_u32_e32 vcc, v11, v136
	v_cmp_gt_i32_e64 s[0:1], v11, v146
	s_and_b64 vcc, vcc, s[0:1]
	v_add_u32_e32 v0, 54, v0
	v_cndmask_b32_e32 v178, v166, v15, vcc
	v_cmp_le_u32_e32 vcc, v0, v136
	v_cmp_gt_i32_e64 s[0:1], v0, v146
	s_and_b64 vcc, vcc, s[0:1]
	v_or_b32_e32 v0, 55, v99
	v_cndmask_b32_e32 v183, v166, v16, vcc
	v_cmp_le_u32_e32 vcc, v0, v136
	v_cmp_gt_i32_e64 s[0:1], v0, v146
	v_max3_f32 v0, v18, s8, v19
	v_max3_f32 v0, v0, v20, v21
	v_max3_f32 v0, v0, v22, v23
	v_max3_f32 v0, v0, v24, v25
	v_max3_f32 v0, v0, v26, v27
	v_max3_f32 v0, v0, v28, v29
	v_max3_f32 v0, v0, v30, v31
	v_max3_f32 v0, v0, v32, v33
	v_max3_f32 v0, v0, v2, v3
	v_max3_f32 v0, v0, v4, v5
	v_max3_f32 v0, v0, v6, v7
	v_max3_f32 v0, v0, v8, v9
	v_max3_f32 v0, v0, v10, v101
	s_and_b64 vcc, vcc, s[0:1]
	v_max3_f32 v0, v0, v150, v151
	v_cndmask_b32_e32 v99, v166, v17, vcc
	v_max3_f32 v0, v0, v174, v178
	v_max3_f32 v0, v0, v183, v99
	v_mul_f32_e32 v0, 0x3e38aa3b, v0
	v_max_f32_e32 v0, v149, v0
	ds_bpermute_b32 v11, v173, v0
	s_mov_b64 s[0:1], 0
	s_waitcnt lgkmcnt(0)
	s_mov_b64 s[100:101], exec
	s_mov_b64 exec, 1
	ds_write_b32 v252, v254
	s_mov_b64 exec, s[100:101]
	v_max_f32_e32 v11, v11, v11
	v_max_f32_e32 v0, v0, v11
	v_fma_f32 v11, v18, s33, -v0
	v_exp_f32_e32 v18, v11
	v_fma_f32 v11, v19, s33, -v0
	v_exp_f32_e32 v19, v11
	v_fma_f32 v11, v20, s33, -v0
	v_exp_f32_e32 v20, v11
	v_fma_f32 v13, v21, s33, -v0
	v_exp_f32_e32 v21, v13
	v_fma_f32 v13, v22, s33, -v0
	v_add_f32_e32 v12, 0, v18
	v_exp_f32_e32 v22, v13
	v_fma_f32 v13, v23, s33, -v0
	v_add_f32_e32 v12, v19, v12
	v_exp_f32_e32 v23, v13
	v_fma_f32 v13, v24, s33, -v0
	v_add_f32_e32 v12, v20, v12
	v_exp_f32_e32 v24, v13
	v_fma_f32 v13, v25, s33, -v0
	v_add_f32_e32 v12, v21, v12
	v_exp_f32_e32 v25, v13
	v_fma_f32 v13, v26, s33, -v0
	v_add_f32_e32 v12, v22, v12
	v_exp_f32_e32 v188, v13
	v_fma_f32 v13, v27, s33, -v0
	v_add_f32_e32 v12, v23, v12
	v_exp_f32_e32 v189, v13
	v_fma_f32 v13, v28, s33, -v0
	v_add_f32_e32 v12, v24, v12
	v_exp_f32_e32 v190, v13
	v_fma_f32 v13, v29, s33, -v0
	v_add_f32_e32 v12, v25, v12
	v_exp_f32_e32 v191, v13
	v_fma_f32 v13, v30, s33, -v0
	v_add_f32_e32 v12, v188, v12
	v_exp_f32_e32 v194, v13
	v_fma_f32 v13, v31, s33, -v0
	v_add_f32_e32 v12, v189, v12
	v_exp_f32_e32 v195, v13
	v_fma_f32 v13, v32, s33, -v0
	v_add_f32_e32 v12, v190, v12
	v_exp_f32_e32 v196, v13
	v_fma_f32 v13, v33, s33, -v0
	v_add_f32_e32 v12, v191, v12
	v_exp_f32_e32 v197, v13
	v_fma_f32 v2, v2, s33, -v0
	v_add_f32_e32 v12, v194, v12
	v_exp_f32_e32 v198, v2
	v_fma_f32 v2, v3, s33, -v0
	v_add_f32_e32 v12, v195, v12
	v_exp_f32_e32 v199, v2
	v_fma_f32 v2, v4, s33, -v0
	v_add_f32_e32 v12, v196, v12
	v_exp_f32_e32 v200, v2
	v_fma_f32 v3, v5, s33, -v0
	v_add_f32_e32 v2, v197, v12
	v_exp_f32_e32 v201, v3
	v_fma_f32 v3, v6, s33, -v0
	v_add_f32_e32 v2, v198, v2
	v_exp_f32_e32 v202, v3
	v_fma_f32 v3, v7, s33, -v0
	v_add_f32_e32 v2, v199, v2
	v_exp_f32_e32 v203, v3
	v_fma_f32 v3, v8, s33, -v0
	v_add_f32_e32 v2, v200, v2
	v_exp_f32_e32 v204, v3
	v_sub_f32_e32 v11, v148, v0
	v_add_f32_e32 v2, v201, v2
	v_add_f32_e32 v2, v202, v2
	v_exp_f32_e32 v100, v11
	v_add_f32_e32 v2, v203, v2
	v_add_f32_e32 v205, v204, v2
	v_fma_f32 v2, v9, s33, -v0
	v_exp_f32_e32 v206, v2
	v_fma_f32 v2, v10, s33, -v0
	v_exp_f32_e32 v207, v2
	v_pk_mul_f32 v[16:17], v[144:145], v[100:101] op_sel_hi:[1,0]
	v_pk_mul_f32 v[14:15], v[140:141], v[100:101] op_sel_hi:[1,0]
	v_pk_mul_f32 v[12:13], v[132:133], v[100:101] op_sel_hi:[1,0]
	v_pk_mul_f32 v[10:11], v[130:131], v[100:101] op_sel_hi:[1,0]
	v_pk_mul_f32 v[8:9], v[128:129], v[100:101] op_sel_hi:[1,0]
	v_pk_mul_f32 v[6:7], v[126:127], v[100:101] op_sel_hi:[1,0]
	v_pk_mul_f32 v[4:5], v[124:125], v[100:101] op_sel_hi:[1,0]
	v_pk_mul_f32 v[2:3], v[122:123], v[100:101] op_sel_hi:[1,0]
	v_pk_mul_f32 v[32:33], v[142:143], v[100:101] op_sel_hi:[1,0]
	v_cvt_pk_bf16_f32 v184, v18, v19
	v_cvt_pk_bf16_f32 v185, v20, v21
	v_cvt_pk_bf16_f32 v186, v22, v23
	v_cvt_pk_bf16_f32 v187, v24, v25
	v_pk_mul_f32 v[30:31], v[120:121], v[100:101] op_sel_hi:[1,0]
	v_pk_mul_f32 v[28:29], v[118:119], v[100:101] op_sel_hi:[1,0]
	v_pk_mul_f32 v[26:27], v[116:117], v[100:101] op_sel_hi:[1,0]
	v_pk_mul_f32 v[24:25], v[114:115], v[100:101] op_sel_hi:[1,0]
	v_pk_mul_f32 v[22:23], v[112:113], v[100:101] op_sel_hi:[1,0]
	v_pk_mul_f32 v[20:21], v[110:111], v[100:101] op_sel_hi:[1,0]
	v_pk_mul_f32 v[18:19], v[108:109], v[100:101] op_sel_hi:[1,0]
	v_mfma_f32_32x32x16_bf16 v[2:17], v[94:97], v[184:187], v[2:17]
	v_fma_f32 v95, v101, s33, -v0
	v_mfma_f32_32x32x16_bf16 v[18:33], v[90:93], v[184:187], v[18:33]
	v_add_f32_e32 v90, v206, v205
	v_add_f32_e32 v94, v207, v90
	v_cvt_pk_bf16_f32 v90, v188, v189
	v_cvt_pk_bf16_f32 v91, v190, v191
	v_cvt_pk_bf16_f32 v92, v194, v195
	v_cvt_pk_bf16_f32 v93, v196, v197
	s_nop 1
	v_mfma_f32_32x32x16_bf16 v[2:17], v[70:73], v[90:93], v[2:17]
	v_exp_f32_e32 v70, v95
	v_fma_f32 v71, v150, s33, -v0
	v_exp_f32_e32 v71, v71
	v_fma_f32 v72, v151, s33, -v0
	v_exp_f32_e32 v72, v72
	v_add_f32_e32 v73, v70, v94
	v_add_f32_e32 v73, v71, v73
	v_mfma_f32_32x32x16_bf16 v[18:33], v[66:69], v[90:93], v[18:33]
	v_fma_f32 v66, v174, s33, -v0
	v_exp_f32_e32 v90, v66
	v_cvt_pk_bf16_f32 v66, v198, v199
	v_cvt_pk_bf16_f32 v67, v200, v201
	v_cvt_pk_bf16_f32 v68, v202, v203
	v_cvt_pk_bf16_f32 v69, v204, v206
	v_add_f32_e32 v73, v72, v73
	s_nop 0
	v_mfma_f32_32x32x16_bf16 v[2:17], v[62:65], v[66:69], v[2:17]
	v_fma_f32 v63, v178, s33, -v0
	v_exp_f32_e32 v63, v63
	v_fma_f32 v64, v183, s33, -v0
	v_exp_f32_e32 v64, v64
	v_fma_f32 v65, v99, s33, -v0
	v_exp_f32_e32 v65, v65
	v_add_f32_e32 v62, v90, v73
	v_mfma_f32_32x32x16_bf16 v[18:33], v[58:61], v[66:69], v[18:33]
	v_add_f32_e32 v58, v63, v62
	v_add_f32_e32 v58, v64, v58
	v_add_f32_e32 v62, v65, v58
	v_cvt_pk_bf16_f32 v58, v207, v70
	v_cvt_pk_bf16_f32 v59, v71, v72
	v_cvt_pk_bf16_f32 v60, v90, v63
	v_cvt_pk_bf16_f32 v61, v64, v65
	s_nop 1
	v_mfma_f32_32x32x16_bf16 v[2:17], v[38:41], v[58:61], v[2:17]
	s_nop 1
	v_mfma_f32_32x32x16_bf16 v[18:33], v[34:37], v[58:61], v[18:33]
	v_fma_f32 v40, v147, v100, v62
; #define MFMA(a, b, c) __builtin_amdgcn_mfma_f32_32x32x16_bf16((a), (b), (c), 0, 0, 0)
; DI unsigned pack2(float a, float b) { f32x2_t v = {a, b}; bf16x2_t r = __builtin_convertvector(v, bf16x2_t); return __builtin_bit_cast(unsigned, r); }
; DI float fexp2(float x) { return __builtin_amdgcn_exp2f(x); }
; template <int DQK, bool MASKED, int MODE, class MF>
; DI void attn_step(const bf16_t* sK, const bf16_t* sVt, const bf16x8 (&qf)[DQK / 16], f32x16& o0, f32x16& o1, float& m, float& l,
;                   float sc, const MF& mf, int lane, f32x16 (&s)[2], float invl, bool lanevalid = true) {
;     ...
;   float mxr = -3.0e38f;
; #pragma unroll
;   for (int sub = 0; sub < 2; ++sub)
; #pragma unroll
;     for (int q = 0; q < 16; ++q) {
;       if (MASKED) { const int kk = sub * 32 + 16 * (q >> 3) + 8 * h + (q & 7); s[sub][q] = mf(kk) ? s[sub][q] : -3.0e38f; }
;       if (MODE != 2) mxr = fmaxf(mxr, s[sub][q]);
;     }
;   float alpha = 1.f;
;   if (MODE != 2) {
;     float mx = fmaxf(m, mxr * sc);
;     mx = fmaxf(mx, shx(mx, 32));
;     if (!MASKED) mx = lanevalid ? mx : m;
;     alpha = fexp2(m - mx);
;     m = mx;
;   }
;   const float moff = (!MASKED && !lanevalid) ? 1.0e30f : m;
;   float ps = 0.f;
; #pragma unroll
;   for (int sub = 0; sub < 2; ++sub)
; #pragma unroll
;     for (int q = 0; q < 16; ++q) {
;       float pv = fexp2(__builtin_fmaf(s[sub][q], sc, -moff));
;       if (MASKED && MODE != 0) pv = (s[sub][q] > -1.0e38f) ? pv : 0.f;
;       if (MODE == 2) pv *= invl;
;       s[sub][q] = pv;
;       ps += pv;
;     }
;   if (MODE != 2) {
;     ps += shx(ps, 32);
;     l = l * alpha + ps;
;   }
;   if (MODE == 1) return;
;   if (MODE == 0) {
; #pragma unroll
;     for (int q = 0; q < 16; ++q) { o0[q] *= alpha; o1[q] *= alpha; }
;   }
; #pragma unroll
;   for (int sub = 0; sub < 2; ++sub)
; #pragma unroll
;     for (int s2 = 0; s2 < 2; ++s2) {
;       union { bf16x8 v; unsigned u[4]; } pb;
; #pragma unroll
;       for (int e = 0; e < 4; ++e) pb.u[e] = pack2(s[sub][8 * s2 + 2 * e], s[sub][8 * s2 + 2 * e + 1]);
;       o0 = MFMA(vf[sub][s2][0], pb.v, o0);
;       o1 = MFMA(vf[sub][s2][1], pb.v, o1);
;     }
; DI void phase_attn_nsa(const Params& P, bf16_t* og, unsigned char* smem, int L, int G) {
;     ...
;         else attn_step<64, false, 0>(sK + cb * KVB64, sVt + cb * KVB64, qf, o0, o1, m, l, sc, mf, lane, s, 0.f);
.LBB0_1367:
	s_andn2_b64 vcc, exec, s[0:1]
	s_cbranch_vccnz .LBB0_1369
	v_lshl_add_u32 v0, s5, 1, v182
	s_nop 3
	ds_read_b128 v[2:5], v0
	s_nop 3
	ds_read_b128 v[18:21], v0 offset:32
	ds_read_b128 v[22:25], v0 offset:64
	ds_read_b128 v[58:61], v0 offset:96
	ds_read_b128 v[26:29], v0 offset:4608
	ds_read_b128 v[62:65], v0 offset:4640
	ds_read_b128 v[66:69], v0 offset:4672
	ds_read_b128 v[184:187], v0 offset:4704
	s_waitcnt lgkmcnt(7)
	v_mfma_f32_32x32x16_bf16 v[2:17], v[2:5], v[74:77], 0
	v_add3_u32 v0, v98, v175, v138
	s_waitcnt lgkmcnt(3)
	v_mfma_f32_32x32x16_bf16 v[26:41], v[26:29], v[74:77], 0
	v_mfma_f32_32x32x16_bf16 v[2:17], v[18:21], v[78:81], v[2:17]
	s_waitcnt lgkmcnt(2)
	v_mfma_f32_32x32x16_bf16 v[26:41], v[62:65], v[78:81], v[26:41]
	v_mfma_f32_32x32x16_bf16 v[2:17], v[22:25], v[82:85], v[2:17]
	v_add3_u32 v22, v98, v177, v138
	s_waitcnt lgkmcnt(1)
	v_mfma_f32_32x32x16_bf16 v[26:41], v[66:69], v[82:85], v[26:41]
	v_mfma_f32_32x32x16_bf16 v[2:17], v[58:61], v[86:89], v[2:17]
	ds_read_b128 v[18:21], v0 offset:9216
	ds_read_b128 v[94:97], v0 offset:9248
	ds_read_b128 v[98:101], v22 offset:9216
	ds_read_b128 v[90:93], v22 offset:9248
	ds_read_b128 v[70:73], v0 offset:9280
	ds_read_b128 v[62:65], v0 offset:9312
	ds_read_b128 v[66:69], v22 offset:9280
	ds_read_b128 v[58:61], v22 offset:9312
	s_waitcnt lgkmcnt(8)
	v_mfma_f32_32x32x16_bf16 v[26:41], v[184:187], v[86:89], v[26:41]
	s_nop 1
	v_max3_f32 v0, v2, s8, v3
	v_max3_f32 v0, v0, v4, v5
	v_max3_f32 v0, v0, v6, v7
	v_max3_f32 v0, v0, v8, v9
	v_max3_f32 v0, v0, v10, v11
	v_max3_f32 v0, v0, v12, v13
	v_max3_f32 v0, v0, v14, v15
	v_max3_f32 v0, v0, v16, v17
	s_nop 1
	v_max3_f32 v0, v0, v26, v27
	v_max3_f32 v0, v0, v28, v29
	v_max3_f32 v0, v0, v30, v31
	v_max3_f32 v0, v0, v32, v33
	v_max3_f32 v0, v0, v34, v35
	v_max3_f32 v0, v0, v36, v37
	v_max3_f32 v0, v0, v38, v39
	v_max3_f32 v0, v0, v40, v41
	v_mul_f32_e32 v0, 0x3e38aa3b, v0
	v_max_f32_e32 v0, v149, v0
	ds_bpermute_b32 v22, v173, v0
	s_waitcnt lgkmcnt(0)
	s_mov_b64 s[100:101], exec
	s_mov_b64 exec, 1
	ds_write_b32 v252, v254
	s_mov_b64 exec, s[100:101]
	v_max_f32_e32 v22, v22, v22
	v_max_f32_e32 v0, v0, v22
	v_fma_f32 v2, v2, s33, -v0
	v_fma_f32 v3, v3, s33, -v0
	v_exp_f32_e32 v23, v2
	v_fma_f32 v4, v4, s33, -v0
	v_exp_f32_e32 v24, v3
	v_fma_f32 v5, v5, s33, -v0
	v_exp_f32_e32 v25, v4
	v_exp_f32_e32 v149, v5
	v_fma_f32 v3, v6, s33, -v0
	v_add_f32_e32 v2, 0, v23
	v_exp_f32_e32 v150, v3
	v_fma_f32 v3, v7, s33, -v0
	v_add_f32_e32 v2, v24, v2
	v_exp_f32_e32 v151, v3
	v_fma_f32 v3, v8, s33, -v0
	v_add_f32_e32 v2, v25, v2
	v_exp_f32_e32 v174, v3
	v_fma_f32 v3, v9, s33, -v0
	v_add_f32_e32 v2, v149, v2
	v_exp_f32_e32 v178, v3
	v_fma_f32 v3, v10, s33, -v0
	v_add_f32_e32 v2, v150, v2
	v_exp_f32_e32 v183, v3
	v_fma_f32 v3, v11, s33, -v0
	v_add_f32_e32 v2, v151, v2
	v_exp_f32_e32 v184, v3
	v_fma_f32 v3, v12, s33, -v0
	v_add_f32_e32 v2, v174, v2
	v_exp_f32_e32 v185, v3
	v_fma_f32 v3, v13, s33, -v0
	v_add_f32_e32 v2, v178, v2
	v_exp_f32_e32 v186, v3
	v_fma_f32 v3, v14, s33, -v0
	v_add_f32_e32 v2, v183, v2
	v_exp_f32_e32 v187, v3
	v_fma_f32 v3, v15, s33, -v0
	v_add_f32_e32 v2, v184, v2
	v_exp_f32_e32 v188, v3
	v_fma_f32 v3, v16, s33, -v0
	v_add_f32_e32 v2, v185, v2
	v_exp_f32_e32 v189, v3
	v_fma_f32 v3, v17, s33, -v0
	v_add_f32_e32 v2, v186, v2
	v_exp_f32_e32 v190, v3
	v_fma_f32 v3, v26, s33, -v0
	v_add_f32_e32 v2, v187, v2
	v_exp_f32_e32 v191, v3
	v_fma_f32 v3, v27, s33, -v0
	v_add_f32_e32 v2, v188, v2
	v_exp_f32_e32 v194, v3
	v_fma_f32 v3, v28, s33, -v0
	v_add_f32_e32 v2, v189, v2
	v_exp_f32_e32 v195, v3
	v_fma_f32 v3, v29, s33, -v0
	v_add_f32_e32 v2, v190, v2
	v_exp_f32_e32 v196, v3
	v_fma_f32 v3, v30, s33, -v0
	v_add_f32_e32 v2, v191, v2
	v_exp_f32_e32 v197, v3
	v_fma_f32 v3, v31, s33, -v0
	v_add_f32_e32 v2, v194, v2
	v_exp_f32_e32 v198, v3
	v_fma_f32 v3, v32, s33, -v0
	v_add_f32_e32 v2, v195, v2
	v_exp_f32_e32 v199, v3
	v_sub_f32_e32 v22, v148, v0
	v_add_f32_e32 v2, v196, v2
	v_add_f32_e32 v2, v197, v2
	v_exp_f32_e32 v148, v22
	v_add_f32_e32 v2, v198, v2
	v_add_f32_e32 v200, v199, v2
	v_fma_f32 v2, v33, s33, -v0
	v_exp_f32_e32 v201, v2
	v_fma_f32 v2, v34, s33, -v0
	v_exp_f32_e32 v202, v2
	v_pk_mul_f32 v[16:17], v[144:145], v[148:149] op_sel_hi:[1,0]
	v_pk_mul_f32 v[14:15], v[140:141], v[148:149] op_sel_hi:[1,0]
	v_pk_mul_f32 v[12:13], v[132:133], v[148:149] op_sel_hi:[1,0]
	v_pk_mul_f32 v[10:11], v[130:131], v[148:149] op_sel_hi:[1,0]
	v_pk_mul_f32 v[8:9], v[128:129], v[148:149] op_sel_hi:[1,0]
	v_pk_mul_f32 v[6:7], v[126:127], v[148:149] op_sel_hi:[1,0]
	v_pk_mul_f32 v[4:5], v[124:125], v[148:149] op_sel_hi:[1,0]
	v_pk_mul_f32 v[2:3], v[122:123], v[148:149] op_sel_hi:[1,0]
	v_cvt_pk_bf16_f32 v122, v23, v24
	v_cvt_pk_bf16_f32 v123, v25, v149
	v_cvt_pk_bf16_f32 v124, v150, v151
	v_cvt_pk_bf16_f32 v125, v174, v178
	v_pk_mul_f32 v[32:33], v[142:143], v[148:149] op_sel_hi:[1,0]
	v_pk_mul_f32 v[30:31], v[120:121], v[148:149] op_sel_hi:[1,0]
	v_mfma_f32_32x32x16_bf16 v[2:17], v[18:21], v[122:125], v[2:17]
	v_mul_f32_e64 v28, v118, v148
	v_mul_f32_e64 v29, v119, v148
	v_mul_f32_e64 v26, v116, v148
	v_mul_f32_e64 v27, v117, v148
	v_mul_f32_e64 v24, v114, v148
	v_mul_f32_e64 v25, v115, v148
	v_pk_mul_f32 v[22:23], v[112:113], v[148:149] op_sel_hi:[1,0]
	v_pk_mul_f32 v[20:21], v[110:111], v[148:149] op_sel_hi:[1,0]
	v_pk_mul_f32 v[18:19], v[108:109], v[148:149] op_sel_hi:[1,0]
	v_fma_f32 v35, v35, s33, -v0
	v_add_f32_e32 v34, v201, v200
	v_mfma_f32_32x32x16_bf16 v[18:33], v[98:101], v[122:125], v[18:33]
	v_cvt_pk_bf16_f32 v98, v183, v184
	v_cvt_pk_bf16_f32 v99, v185, v186
	v_cvt_pk_bf16_f32 v100, v187, v188
	v_cvt_pk_bf16_f32 v101, v189, v190
	v_add_f32_e32 v34, v202, v34
	v_fma_f32 v39, v39, s33, -v0
	v_exp_f32_e32 v39, v39
	v_mfma_f32_32x32x16_bf16 v[2:17], v[94:97], v[98:101], v[2:17]
	v_exp_f32_e32 v94, v35
	v_fma_f32 v35, v36, s33, -v0
	v_exp_f32_e32 v95, v35
	v_fma_f32 v35, v37, s33, -v0
	v_exp_f32_e32 v96, v35
	v_add_f32_e32 v34, v94, v34
	v_add_f32_e32 v34, v95, v34
	v_mfma_f32_32x32x16_bf16 v[18:33], v[90:93], v[98:101], v[18:33]
	v_add_f32_e32 v90, v96, v34
	v_fma_f32 v34, v38, s33, -v0
	v_exp_f32_e32 v38, v34
	v_cvt_pk_bf16_f32 v34, v191, v194
	v_cvt_pk_bf16_f32 v35, v195, v196
	v_cvt_pk_bf16_f32 v36, v197, v198
	v_cvt_pk_bf16_f32 v37, v199, v201
	v_fma_f32 v40, v40, s33, -v0
	v_exp_f32_e32 v40, v40
	v_mfma_f32_32x32x16_bf16 v[2:17], v[70:73], v[34:37], v[2:17]
	v_fma_f32 v41, v41, s33, -v0
	v_exp_f32_e32 v41, v41
	v_add_f32_e32 v70, v38, v90
	v_mfma_f32_32x32x16_bf16 v[18:33], v[66:69], v[34:37], v[18:33]
	v_add_f32_e32 v34, v39, v70
	v_add_f32_e32 v34, v40, v34
	v_add_f32_e32 v66, v41, v34
	v_cvt_pk_bf16_f32 v34, v202, v94
	v_cvt_pk_bf16_f32 v35, v95, v96
	v_cvt_pk_bf16_f32 v36, v38, v39
	v_cvt_pk_bf16_f32 v37, v40, v41
	s_nop 1
	v_mfma_f32_32x32x16_bf16 v[2:17], v[62:65], v[34:37], v[2:17]
	v_mfma_f32_32x32x16_bf16 v[18:33], v[58:61], v[34:37], v[18:33]
	v_fma_f32 v40, v147, v148, v66
